# ADIFF item prologue: K/V chunk 0/1 LDS-DMA issued at the item top, before the Q loads and reference-point arithmetic
# baseline (speedup 1.0000x reference)
; #define LAS __attribute__((address_space(3)))
; __device__ __forceinline__ void diff_attn_phase(const Params& p, LAS unsigned char* lds) {
;     ...
;         const int h = it & 7, qc = (it >> 3) & 31, b = it >> 8;
;         const size_t tokb = (size_t)b * SEQ;
;         const bf16_t* qp = PROJ + h * 128 + 64 * comp; const bf16_t* kp = PROJ + 1024 + h * 128; const bf16_t* vp = PROJ + 2048 + h * 128; const bf16_t* zp = PROJ + 3072 + h * 128;
;         const int iw = qc * 256 + 64 * wq;
;         bf16x8 qf[2][4];
;         int ln0 = lane; asm volatile("" : "+v"(ln0));
; #pragma unroll
;         for (int r = 0; r < 2; ++r) { const bf16_t* qrow = qp + (tokb + iw + 32 * r + (ln0 & 31)) * ld + 8 * (ln0 >> 5);
; #pragma unroll
;             for (int ks = 0; ks < 4; ++ks) qf[r][ks] = *(const bf16x8*)(qrow + 16 * ks); }
;         f32x16 O[2][4];
; #pragma unroll
;         for (int r = 0; r < 2; ++r)
; #pragma unroll
;             for (int t = 0; t < 4; ++t)
; #pragma unroll
;                 for (int i = 0; i < 16; ++i) O[r][t][i] = 0.f;
;         float m[2], l[2] = {0.f, 0.f};
;         { const float kmx = __uint_as_float(((const unsigned*)(p.ws + WS_KMAX))[b * 16 + h * 2 + comp]);
; #pragma unroll
;           for (int r = 0; r < 2; ++r) { float s = 0.f;
; #pragma unroll
;               for (int ks = 0; ks < 4; ++ks) { const u32x4 qv = __builtin_bit_cast(u32x4, qf[r][ks]);
; #pragma unroll
;                   for (int i = 0; i < 4; ++i) { const float x0 = bf_lo(qv[i]), x1 = bf_hi(qv[i]); s += x0 * x0 + x1 * x1; } }
;               m[r] = sqrtf(xsum32(s) * kmx) * 1.001f + 1e-3f; } }
;         bf16x8 kone, qm[2];
;         { const unsigned one = hh == 0 ? 0x3F80u : 0u; kone = __builtin_bit_cast(bf16x8, (u32x4){one, 0u, 0u, 0u});
; #pragma unroll
;           for (int r = 0; r < 2; ++r) { const unsigned mb = hh == 0 ? (pk_bf16(-m[r], 0.f) & 0xffffu) : 0u; qm[r] = __builtin_bit_cast(bf16x8, (u32x4){mb, 0u, 0u, 0u}); } }
;         auto issue = [&](int ch, int stg) {
;             const char* kg = (const char*)(kp + (tokb + 64 * ch) * ld); const char* vg = (const char*)(vp + (tokb + 64 * ch) * ld);
;             LAS unsigned char* sb = lds + stg * STG;
; #pragma unroll
;             for (int i = 0; i < 2; ++i) { unsigned o = doff[i]; asm volatile("" : "+v"(o));
;                 __builtin_amdgcn_global_load_lds((const void*)(kg + o), (LAS void*)(sb + dlds[i]), 16, 0, 0);
.LBB0_38:
	s_ashr_i32 s46, s57, 8
	s_and_b32 s5, s57, 7
	s_ashr_i32 s47, s46, 31
	s_lshl_b64 s[26:27], s[46:47], 13
	s_lshl_b32 s35, s5, 8
	s_add_u32 s22, s36, s35
	s_addc_u32 s23, s70, 0
	s_add_u32 s25, s78, s35
	s_addc_u32 s28, s83, 0
	s_lshl_b64 s[10:11], s[46:47], 26
	s_add_u32 s42, s25, s10
	s_addc_u32 s43, s28, s11
	s_add_u32 s52, s22, s10
	s_addc_u32 s53, s23, s11
	v_readfirstlane_b32 s2, v242
	v_readfirstlane_b32 s4, v244
	s_mov_b32 m0, s2
	s_nop 0
	global_load_lds_dwordx4 v241, s[42:43]
	s_add_i32 s35, s2, 0x4000
	s_mov_b32 m0, s35
	s_nop 0
	global_load_lds_dwordx4 v241, s[52:53]
	s_mov_b32 m0, s4
	s_nop 0
	global_load_lds_dwordx4 v243, s[42:43]
	s_add_i32 s35, s4, 0x4000
	s_mov_b32 m0, s35
	s_nop 0
	global_load_lds_dwordx4 v243, s[52:53]
	s_or_b32 s35, s10, 0x80000
	s_add_u32 s42, s25, s35
	s_addc_u32 s43, s28, s11
	s_add_u32 s10, s22, s35
	s_addc_u32 s11, s23, s11
	s_add_i32 s35, s2, 0x8000
	s_mov_b32 m0, s35
	s_nop 0
	global_load_lds_dwordx4 v241, s[42:43]
	s_add_i32 s35, s2, 0xc000
	s_mov_b32 m0, s35
	s_nop 0
	global_load_lds_dwordx4 v241, s[10:11]
	s_add_i32 s35, s4, 0x8000
	s_mov_b32 m0, s35
	s_nop 0
	global_load_lds_dwordx4 v243, s[42:43]
	s_add_i32 s35, s4, 0xc000
	s_mov_b32 m0, s35
	s_nop 0
	global_load_lds_dwordx4 v243, s[10:11]
	s_lshl_b32 s2, s5, 8
	s_add_u32 s10, s21, s2
	s_addc_u32 s11, s54, 0
	s_lshl_b32 s2, s57, 5
	s_and_b32 s2, s2, 0x1f00
	v_mov_b32_e32 v1, v240
	s_or_b32 s4, s2, s55
	v_mov_b32_e32 v5, s27
	v_and_or_b32 v4, v1, 31, s4
	v_ashrrev_i32_e32 v1, 2, v1
	v_and_b32_e32 v2, -8, v1
	v_ashrrev_i32_e32 v3, 31, v2
	v_or_b32_e32 v4, s26, v4
	v_lshl_add_u64 v[2:3], v[2:3], 1, s[10:11]
	v_lshlrev_b64 v[6:7], 13, v[4:5]
	v_lshl_add_u64 v[6:7], v[2:3], 0, v[6:7]
	global_load_dwordx4 v[166:169], v[6:7], off
	global_load_dwordx4 v[170:173], v[6:7], off offset:32
	global_load_dwordx4 v[174:177], v[6:7], off offset:64
	global_load_dwordx4 v[178:181], v[6:7], off offset:96
	v_or_b32_e32 v4, 32, v4
	v_lshlrev_b64 v[4:5], 13, v[4:5]
	v_lshl_add_u64 v[2:3], v[2:3], 0, v[4:5]
	global_load_dwordx4 v[182:185], v[2:3], off
	global_load_dwordx4 v[186:189], v[2:3], off offset:32
	global_load_dwordx4 v[190:193], v[2:3], off offset:64
	global_load_dwordx4 v[194:197], v[2:3], off offset:96
	s_lshl_b32 s10, s5, 1
	s_lshl_b32 s2, s46, 4
	s_add_i32 s10, s10, s15
	s_add_i32 s10, s10, s2
	s_ashr_i32 s11, s10, 31
	s_lshl_b64 s[10:11], s[10:11], 2
	s_add_u32 s42, s12, s10
	s_addc_u32 s43, s13, s11
	v_mov_b32_e32 v198, 0
	global_load_dword v1, v198, s[42:43]
	s_waitcnt vmcnt(0)
	v_and_b32_e32 v3, 0xffff0000, v166
	v_lshlrev_b32_e32 v2, 16, v166
	v_mul_f32_e32 v3, v3, v3
	v_and_b32_e32 v4, 0xffff0000, v167
	v_fmac_f32_e32 v3, v2, v2
	v_lshlrev_b32_e32 v2, 16, v167
	v_mul_f32_e32 v4, v4, v4
	v_fmac_f32_e32 v4, v2, v2
	v_add_f32_e32 v2, v3, v4
	v_and_b32_e32 v4, 0xffff0000, v168
	v_lshlrev_b32_e32 v3, 16, v168
	v_mul_f32_e32 v4, v4, v4
	v_fmac_f32_e32 v4, v3, v3
	v_add_f32_e32 v2, v4, v2
	v_and_b32_e32 v4, 0xffff0000, v169
	v_lshlrev_b32_e32 v3, 16, v169
	v_mul_f32_e32 v4, v4, v4
	v_fmac_f32_e32 v4, v3, v3
	v_add_f32_e32 v2, v4, v2
	s_waitcnt vmcnt(7)
	v_and_b32_e32 v4, 0xffff0000, v170
	v_lshlrev_b32_e32 v3, 16, v170
	v_mul_f32_e32 v4, v4, v4
	v_fmac_f32_e32 v4, v3, v3
	v_add_f32_e32 v2, v4, v2
	v_and_b32_e32 v4, 0xffff0000, v171
	v_lshlrev_b32_e32 v3, 16, v171
	v_mul_f32_e32 v4, v4, v4
	v_fmac_f32_e32 v4, v3, v3
	v_add_f32_e32 v2, v4, v2
	v_and_b32_e32 v4, 0xffff0000, v172
	v_lshlrev_b32_e32 v3, 16, v172
	v_mul_f32_e32 v4, v4, v4
	v_fmac_f32_e32 v4, v3, v3
	v_add_f32_e32 v2, v4, v2
	v_and_b32_e32 v4, 0xffff0000, v173
	v_lshlrev_b32_e32 v3, 16, v173
	v_mul_f32_e32 v4, v4, v4
	v_fmac_f32_e32 v4, v3, v3
	v_add_f32_e32 v2, v4, v2
	s_waitcnt vmcnt(6)
	v_and_b32_e32 v4, 0xffff0000, v174
	v_lshlrev_b32_e32 v3, 16, v174
	v_mul_f32_e32 v4, v4, v4
	v_fmac_f32_e32 v4, v3, v3
	v_add_f32_e32 v2, v4, v2
	v_and_b32_e32 v4, 0xffff0000, v175
	v_lshlrev_b32_e32 v3, 16, v175
	v_mul_f32_e32 v4, v4, v4
	v_fmac_f32_e32 v4, v3, v3
	v_add_f32_e32 v2, v4, v2
	v_and_b32_e32 v4, 0xffff0000, v176
	v_lshlrev_b32_e32 v3, 16, v176
	v_mul_f32_e32 v4, v4, v4
	v_fmac_f32_e32 v4, v3, v3
	v_add_f32_e32 v2, v4, v2
	v_and_b32_e32 v4, 0xffff0000, v177
	v_lshlrev_b32_e32 v3, 16, v177
	v_mul_f32_e32 v4, v4, v4
	v_fmac_f32_e32 v4, v3, v3
	v_add_f32_e32 v2, v4, v2
	s_waitcnt vmcnt(5)
	v_and_b32_e32 v4, 0xffff0000, v178
	v_lshlrev_b32_e32 v3, 16, v178
	v_mul_f32_e32 v4, v4, v4
	v_fmac_f32_e32 v4, v3, v3
	v_add_f32_e32 v2, v4, v2
	v_and_b32_e32 v4, 0xffff0000, v179
	v_lshlrev_b32_e32 v3, 16, v179
	v_mul_f32_e32 v4, v4, v4
	v_fmac_f32_e32 v4, v3, v3
	v_add_f32_e32 v2, v4, v2
	v_and_b32_e32 v4, 0xffff0000, v180
	v_lshlrev_b32_e32 v3, 16, v180
	v_mul_f32_e32 v4, v4, v4
	v_fmac_f32_e32 v4, v3, v3
	v_add_f32_e32 v2, v4, v2
	v_and_b32_e32 v4, 0xffff0000, v181
	v_lshlrev_b32_e32 v3, 16, v181
	v_mul_f32_e32 v4, v4, v4
	v_fmac_f32_e32 v4, v3, v3
	s_waitcnt vmcnt(4)
	v_and_b32_e32 v3, 0xffff0000, v182
	v_add_f32_e32 v4, v4, v2
	v_lshlrev_b32_e32 v2, 16, v182
	v_mul_f32_e32 v3, v3, v3
	v_and_b32_e32 v6, 0xffff0000, v183
	v_fmac_f32_e32 v3, v2, v2
	v_lshlrev_b32_e32 v2, 16, v183
	v_mul_f32_e32 v6, v6, v6
	v_fmac_f32_e32 v6, v2, v2
	v_add_f32_e32 v2, v3, v6
	v_and_b32_e32 v6, 0xffff0000, v184
	v_lshlrev_b32_e32 v3, 16, v184
	v_mul_f32_e32 v6, v6, v6
	v_fmac_f32_e32 v6, v3, v3
	v_add_f32_e32 v2, v6, v2
	v_and_b32_e32 v6, 0xffff0000, v185
	v_lshlrev_b32_e32 v3, 16, v185
	v_mul_f32_e32 v6, v6, v6
	v_fmac_f32_e32 v6, v3, v3
	v_add_f32_e32 v2, v6, v2
	s_waitcnt vmcnt(3)
; #define LAS __attribute__((address_space(3)))
; __device__ __forceinline__ unsigned pk_bf16(float lo, float hi) { const f32x2 v = {lo, hi}; const bf16v2 b = __builtin_convertvector(v, bf16v2); return __builtin_bit_cast(unsigned, b); }
; __device__ __forceinline__ float bf_lo(unsigned u) { return __uint_as_float(u << 16); }
; __device__ __forceinline__ float bf_hi(unsigned u) { return __uint_as_float(u & 0xffff0000u); }
; __device__ __forceinline__ float xsum32(float v) { const auto r = __builtin_amdgcn_permlane32_swap(__float_as_uint(v), __float_as_uint(v), false, false); return __uint_as_float(r[0]) + __uint_as_float(r[1]); }
; __device__ __forceinline__ void diff_attn_phase(const Params& p, LAS unsigned char* lds) {
;     ...
;           for (int r = 0; r < 2; ++r) { float s = 0.f;
; #pragma unroll
;               for (int ks = 0; ks < 4; ++ks) { const u32x4 qv = __builtin_bit_cast(u32x4, qf[r][ks]);
; #pragma unroll
;                   for (int i = 0; i < 4; ++i) { const float x0 = bf_lo(qv[i]), x1 = bf_hi(qv[i]); s += x0 * x0 + x1 * x1; } }
;               m[r] = sqrtf(xsum32(s) * kmx) * 1.001f + 1e-3f; } }
;         bf16x8 kone, qm[2];
;         { const unsigned one = hh == 0 ? 0x3F80u : 0u; kone = __builtin_bit_cast(bf16x8, (u32x4){one, 0u, 0u, 0u});
; #pragma unroll
;           for (int r = 0; r < 2; ++r) { const unsigned mb = hh == 0 ? (pk_bf16(-m[r], 0.f) & 0xffffu) : 0u; qm[r] = __builtin_bit_cast(bf16x8, (u32x4){mb, 0u, 0u, 0u}); } }
;         auto issue = [&](int ch, int stg) {
;             const char* kg = (const char*)(kp + (tokb + 64 * ch) * ld); const char* vg = (const char*)(vp + (tokb + 64 * ch) * ld);
;             LAS unsigned char* sb = lds + stg * STG;
; #pragma unroll
;             for (int i = 0; i < 2; ++i) { unsigned o = doff[i]; asm volatile("" : "+v"(o));
;                 __builtin_amdgcn_global_load_lds((const void*)(kg + o), (LAS void*)(sb + dlds[i]), 16, 0, 0);
;                 __builtin_amdgcn_global_load_lds((const void*)(vg + o), (LAS void*)(sb + 16384 + dlds[i]), 16, 0, 0); }
;         };
;         issue(0, 0); issue(1, 1);
	v_and_b32_e32 v6, 0xffff0000, v186
	v_lshlrev_b32_e32 v3, 16, v186
	v_mul_f32_e32 v6, v6, v6
	v_fmac_f32_e32 v6, v3, v3
	v_add_f32_e32 v2, v6, v2
	v_and_b32_e32 v6, 0xffff0000, v187
	v_lshlrev_b32_e32 v3, 16, v187
	v_mul_f32_e32 v6, v6, v6
	v_fmac_f32_e32 v6, v3, v3
	v_add_f32_e32 v2, v6, v2
	v_and_b32_e32 v6, 0xffff0000, v188
	v_lshlrev_b32_e32 v3, 16, v188
	v_mul_f32_e32 v6, v6, v6
	v_fmac_f32_e32 v6, v3, v3
	v_add_f32_e32 v2, v6, v2
	v_and_b32_e32 v6, 0xffff0000, v189
	v_lshlrev_b32_e32 v3, 16, v189
	v_mul_f32_e32 v6, v6, v6
	v_fmac_f32_e32 v6, v3, v3
	v_add_f32_e32 v2, v6, v2
	s_waitcnt vmcnt(2)
	v_and_b32_e32 v6, 0xffff0000, v190
	v_lshlrev_b32_e32 v3, 16, v190
	v_mul_f32_e32 v6, v6, v6
	v_fmac_f32_e32 v6, v3, v3
	v_add_f32_e32 v2, v6, v2
	v_and_b32_e32 v6, 0xffff0000, v191
	v_lshlrev_b32_e32 v3, 16, v191
	v_mul_f32_e32 v6, v6, v6
	v_fmac_f32_e32 v6, v3, v3
	v_add_f32_e32 v2, v6, v2
	v_and_b32_e32 v6, 0xffff0000, v192
	v_lshlrev_b32_e32 v3, 16, v192
	v_mul_f32_e32 v6, v6, v6
	v_fmac_f32_e32 v6, v3, v3
	v_add_f32_e32 v2, v6, v2
	v_and_b32_e32 v6, 0xffff0000, v193
	v_lshlrev_b32_e32 v3, 16, v193
	v_mul_f32_e32 v6, v6, v6
	v_fmac_f32_e32 v6, v3, v3
	v_add_f32_e32 v2, v6, v2
	s_waitcnt vmcnt(1)
	v_and_b32_e32 v6, 0xffff0000, v194
	v_lshlrev_b32_e32 v3, 16, v194
	v_mul_f32_e32 v6, v6, v6
	v_fmac_f32_e32 v6, v3, v3
	v_add_f32_e32 v2, v6, v2
	v_and_b32_e32 v6, 0xffff0000, v195
	v_lshlrev_b32_e32 v3, 16, v195
	v_mul_f32_e32 v6, v6, v6
	v_fmac_f32_e32 v6, v3, v3
	v_add_f32_e32 v2, v6, v2
	v_and_b32_e32 v6, 0xffff0000, v196
	v_lshlrev_b32_e32 v3, 16, v196
	v_mul_f32_e32 v6, v6, v6
	v_fmac_f32_e32 v6, v3, v3
	v_add_f32_e32 v2, v6, v2
	v_and_b32_e32 v6, 0xffff0000, v197
	v_lshlrev_b32_e32 v3, 16, v197
	v_mul_f32_e32 v6, v6, v6
	v_fmac_f32_e32 v6, v3, v3
	v_add_f32_e32 v2, v6, v2
	v_mov_b32_e32 v5, v4
	v_mov_b32_e32 v3, v2
	s_nop 0
	v_permlane32_swap_b32_e32 v4, v5
	v_permlane32_swap_b32_e32 v2, v3
	s_and_saveexec_b64 s[52:53], s[40:41]
	s_cbranch_execz .LBB0_40
	v_add_f32_e32 v4, v4, v5
	s_waitcnt vmcnt(0)
	v_mul_f32_e32 v4, v1, v4
	v_mul_f32_e32 v5, 0x4f800000, v4
	v_cmp_gt_f32_e32 vcc, s65, v4
	s_nop 1
	v_cndmask_b32_e32 v4, v4, v5, vcc
	v_sqrt_f32_e32 v5, v4
	s_nop 0
	v_add_u32_e32 v6, -1, v5
	v_fma_f32 v8, -v6, v5, v4
	v_add_u32_e32 v7, 1, v5
	v_cmp_ge_f32_e64 s[42:43], 0, v8
	s_nop 1
	v_cndmask_b32_e64 v6, v5, v6, s[42:43]
	v_fma_f32 v5, -v7, v5, v4
	v_cmp_lt_f32_e64 s[42:43], 0, v5
	s_nop 1
	v_cndmask_b32_e64 v5, v6, v7, s[42:43]
	v_mul_f32_e32 v6, 0x37800000, v5
	v_cndmask_b32_e32 v5, v5, v6, vcc
	v_cmp_class_f32_e32 vcc, v4, v249
	s_nop 1
	v_cndmask_b32_e32 v4, v5, v4, vcc
	v_fmamk_f32 v4, v4, 0x3f8020c5, v252
	v_xor_b32_e32 v4, 0x80000000, v4
	v_cvt_pk_bf16_f32 v4, v4, 0
	v_and_b32_e32 v198, 0xffff, v4
.LBB0_40:
	s_or_b64 exec, exec, s[52:53]
	s_lshl_b32 s2, s5, 7
	s_lshl_b32 s5, s2, 1
	v_add_f32_e32 v2, v2, v3
	s_waitcnt vmcnt(0)
	v_mul_f32_e32 v1, v1, v2
	v_mul_f32_e32 v2, 0x4f800000, v1
	v_cmp_gt_f32_e32 vcc, s65, v1
	v_mov_b32_e32 v66, v0
	v_mov_b32_e32 v67, v0
	v_cndmask_b32_e32 v1, v1, v2, vcc
	v_sqrt_f32_e32 v2, v1
	v_mov_b32_e32 v80, v0
	v_mov_b32_e32 v81, v0
	v_mov_b32_e32 v68, v0
	v_add_u32_e32 v3, -1, v2
	v_fma_f32 v4, -v3, v2, v1
	v_cmp_ge_f32_e64 s[42:43], 0, v4
	v_add_u32_e32 v4, 1, v2
	v_mov_b32_e32 v69, v0
	v_cndmask_b32_e64 v3, v2, v3, s[42:43]
	v_fma_f32 v2, -v4, v2, v1
	v_cmp_lt_f32_e64 s[42:43], 0, v2
	v_mov_b32_e32 v70, v0
	v_mov_b32_e32 v71, v0
	v_cndmask_b32_e64 v2, v3, v4, s[42:43]
	v_mul_f32_e32 v3, 0x37800000, v2
	v_cndmask_b32_e32 v2, v2, v3, vcc
	v_cmp_class_f32_e32 vcc, v1, v249
	v_mov_b32_e32 v72, v0
	v_mov_b32_e32 v73, v0
	v_cndmask_b32_e32 v1, v2, v1, vcc
	v_fmamk_f32 v1, v1, 0x3f8020c5, v252
	v_xor_b32_e32 v1, 0x80000000, v1
	v_cvt_pk_bf16_f32 v1, v1, 0
	v_and_b32_e32 v1, 0xffff, v1
	v_cndmask_b32_e64 v202, 0, v1, s[40:41]
	v_mov_b32_e32 v1, v0
	v_mov_b32_e32 v74, v0
	v_mov_b32_e32 v75, v0
	v_mov_b32_e32 v76, v0
	v_mov_b32_e32 v77, v0
	v_mov_b32_e32 v78, v0
	v_mov_b32_e32 v79, v0
	v_mov_b64_e32 v[96:97], v[80:81]
	v_mov_b64_e32 v[112:113], v[80:81]
	v_mov_b64_e32 v[128:129], v[80:81]
	v_mov_b64_e32 v[50:51], v[66:67]
	v_mov_b64_e32 v[34:35], v[66:67]
	v_mov_b64_e32 v[18:19], v[66:67]
	v_mov_b64_e32 v[2:3], v[66:67]
	s_mov_b32 s42, 0
	v_mov_b32_e32 v199, v0
	v_mov_b32_e32 v200, v0
	v_mov_b32_e32 v201, v0
	v_mov_b32_e32 v203, v0
	v_mov_b32_e32 v204, v0
	v_mov_b32_e32 v205, v0
	s_mov_b32 s37, 2
	v_mov_b64_e32 v[94:95], v[78:79]
	v_mov_b64_e32 v[92:93], v[76:77]
	v_mov_b64_e32 v[90:91], v[74:75]
	v_mov_b64_e32 v[88:89], v[72:73]
	v_mov_b64_e32 v[86:87], v[70:71]
	v_mov_b64_e32 v[84:85], v[68:69]
	v_mov_b64_e32 v[82:83], v[66:67]
	v_mov_b64_e32 v[110:111], v[78:79]
	v_mov_b64_e32 v[108:109], v[76:77]
	v_mov_b64_e32 v[106:107], v[74:75]
	v_mov_b64_e32 v[104:105], v[72:73]
	v_mov_b64_e32 v[102:103], v[70:71]
	v_mov_b64_e32 v[100:101], v[68:69]
	v_mov_b64_e32 v[98:99], v[66:67]
	v_mov_b64_e32 v[126:127], v[78:79]
	v_mov_b64_e32 v[124:125], v[76:77]
	v_mov_b64_e32 v[122:123], v[74:75]
	v_mov_b64_e32 v[120:121], v[72:73]
	v_mov_b64_e32 v[118:119], v[70:71]
	v_mov_b64_e32 v[116:117], v[68:69]
	v_mov_b64_e32 v[114:115], v[66:67]
	v_mov_b64_e32 v[52:53], v[68:69]
	v_mov_b64_e32 v[54:55], v[70:71]
	v_mov_b64_e32 v[56:57], v[72:73]
	v_mov_b64_e32 v[58:59], v[74:75]
	v_mov_b64_e32 v[60:61], v[76:77]
	v_mov_b64_e32 v[62:63], v[78:79]
	v_mov_b64_e32 v[64:65], v[80:81]
	v_mov_b64_e32 v[36:37], v[68:69]
	v_mov_b64_e32 v[38:39], v[70:71]
	v_mov_b64_e32 v[40:41], v[72:73]
	v_mov_b64_e32 v[42:43], v[74:75]
	v_mov_b64_e32 v[44:45], v[76:77]
	v_mov_b64_e32 v[46:47], v[78:79]
	v_mov_b64_e32 v[48:49], v[80:81]
	v_mov_b64_e32 v[20:21], v[68:69]
	v_mov_b64_e32 v[22:23], v[70:71]
	v_mov_b64_e32 v[24:25], v[72:73]
	v_mov_b64_e32 v[26:27], v[74:75]
	v_mov_b64_e32 v[28:29], v[76:77]
	v_mov_b64_e32 v[30:31], v[78:79]
	v_mov_b64_e32 v[32:33], v[80:81]
	v_mov_b64_e32 v[4:5], v[68:69]
	v_mov_b64_e32 v[6:7], v[70:71]
	v_mov_b64_e32 v[8:9], v[72:73]
	v_mov_b64_e32 v[10:11], v[74:75]
	v_mov_b64_e32 v[12:13], v[76:77]
	v_mov_b64_e32 v[14:15], v[78:79]
	v_mov_b64_e32 v[16:17], v[80:81]
	s_mov_b32 s29, 0
	v_mov_b64_e32 v[212:213], v[0:1]
	v_max_u32_e32 v130, v198, v202
	v_cmp_gt_u32_e32 vcc, 0xc270, v130
	s_nop 3
	s_cmp_eq_u64 vcc, exec
	s_cbranch_scc1 .Lfa_entry
	s_mov_b32 s34, s42
	s_cmpk_eq_i32 s29, 0x7f
	s_mov_b64 s[42:43], -1
	s_cbranch_scc1 .LBB0_43
	s_branch .LBB0_42
